# GEMM K-loop variant: one barrier per K-step (next-next K-step DMA issued after the landing barrier), 1 K-step lead
# baseline (speedup 1.0000x reference)
.Lodwin_loop:
	ds_read_b128 v[148:151], v138 offset:0
	ds_read_b128 v[172:175], v139 offset:16384
	ds_read_b128 v[176:179], v139 offset:18432
	ds_read_b128 v[152:155], v138 offset:2048
	ds_read_b128 v[180:183], v139 offset:20480
	ds_read_b128 v[184:187], v139 offset:22528
	ds_read_b128 v[156:159], v138 offset:4096
	ds_read_b128 v[168:171], v138 offset:6144
	s_waitcnt lgkmcnt(8)
	v_mfma_f32_16x16x32_bf16 v[62:65], v[66:69], v[82:85], v[62:65]
	v_mfma_f32_16x16x32_bf16 v[58:61], v[66:69], v[86:89], v[58:61]
	v_mfma_f32_16x16x32_bf16 v[54:57], v[66:69], v[90:93], v[54:57]
	v_mfma_f32_16x16x32_bf16 v[50:53], v[66:69], v[94:97], v[50:53]
	v_mfma_f32_16x16x32_bf16 v[46:49], v[70:73], v[82:85], v[46:49]
	v_mfma_f32_16x16x32_bf16 v[42:45], v[70:73], v[86:89], v[42:45]
	v_mfma_f32_16x16x32_bf16 v[34:37], v[70:73], v[90:93], v[34:37]
	v_mfma_f32_16x16x32_bf16 v[30:33], v[70:73], v[94:97], v[30:33]
	v_mfma_f32_16x16x32_bf16 v[26:29], v[74:77], v[82:85], v[26:29]
	v_mfma_f32_16x16x32_bf16 v[22:25], v[74:77], v[86:89], v[22:25]
	v_mfma_f32_16x16x32_bf16 v[18:21], v[74:77], v[90:93], v[18:21]
	v_mfma_f32_16x16x32_bf16 v[14:17], v[74:77], v[94:97], v[14:17]
	v_mfma_f32_16x16x32_bf16 v[10:13], v[78:81], v[82:85], v[10:13]
	v_mfma_f32_16x16x32_bf16 v[6:9], v[78:81], v[86:89], v[6:9]
	v_mfma_f32_16x16x32_bf16 v[2:5], v[78:81], v[90:93], v[2:5]
	v_mfma_f32_16x16x32_bf16 v[38:41], v[78:81], v[94:97], v[38:41]
	s_waitcnt lgkmcnt(0)
	v_mfma_f32_16x16x32_bf16 v[62:65], v[148:151], v[172:175], v[62:65]
	v_mfma_f32_16x16x32_bf16 v[58:61], v[148:151], v[176:179], v[58:61]
	v_mfma_f32_16x16x32_bf16 v[54:57], v[148:151], v[180:183], v[54:57]
	v_mfma_f32_16x16x32_bf16 v[50:53], v[148:151], v[184:187], v[50:53]
	v_mfma_f32_16x16x32_bf16 v[46:49], v[152:155], v[172:175], v[46:49]
	v_mfma_f32_16x16x32_bf16 v[42:45], v[152:155], v[176:179], v[42:45]
	v_mfma_f32_16x16x32_bf16 v[34:37], v[152:155], v[180:183], v[34:37]
	v_mfma_f32_16x16x32_bf16 v[30:33], v[152:155], v[184:187], v[30:33]
	s_waitcnt vmcnt(0)
	s_barrier
	ds_read_b128 v[66:69], v136 offset:32768
	ds_read_b128 v[82:85], v137 offset:49152
	ds_read_b128 v[86:89], v137 offset:51200
	ds_read_b128 v[70:73], v136 offset:34816
	ds_read_b128 v[90:93], v137 offset:53248
	ds_read_b128 v[94:97], v137 offset:55296
	ds_read_b128 v[74:77], v136 offset:36864
	ds_read_b128 v[78:81], v136 offset:38912
	s_add_u32 m0, s64, 0x0
	v_mfma_f32_16x16x32_bf16 v[26:29], v[156:159], v[172:175], v[26:29]
	global_load_lds_dwordx4 v140, s[60:61]
	s_add_u32 m0, s64, 0x1000
	v_mfma_f32_16x16x32_bf16 v[22:25], v[156:159], v[176:179], v[22:25]
	global_load_lds_dwordx4 v141, s[60:61]
	s_add_u32 m0, s64, 0x2000
	v_mfma_f32_16x16x32_bf16 v[18:21], v[156:159], v[180:183], v[18:21]
	global_load_lds_dwordx4 v142, s[60:61]
	s_add_u32 m0, s64, 0x3000
	v_mfma_f32_16x16x32_bf16 v[14:17], v[156:159], v[184:187], v[14:17]
	global_load_lds_dwordx4 v143, s[60:61]
	s_add_u32 m0, s64, 0x4000
	v_mfma_f32_16x16x32_bf16 v[10:13], v[168:171], v[172:175], v[10:13]
	global_load_lds_dwordx4 v144, s[62:63]
	s_add_u32 m0, s64, 0x5000
	v_mfma_f32_16x16x32_bf16 v[6:9], v[168:171], v[176:179], v[6:9]
	global_load_lds_dwordx4 v145, s[62:63]
	s_add_u32 m0, s64, 0x6000
	v_mfma_f32_16x16x32_bf16 v[2:5], v[168:171], v[180:183], v[2:5]
	global_load_lds_dwordx4 v146, s[62:63]
	s_add_u32 m0, s64, 0x7000
	v_mfma_f32_16x16x32_bf16 v[38:41], v[168:171], v[184:187], v[38:41]
	global_load_lds_dwordx4 v147, s[62:63]
	s_add_u32 s60, s60, 0x80
	s_addc_u32 s61, s61, 0
	s_add_u32 s62, s62, 0x80
	s_addc_u32 s63, s63, 0
	ds_read_b128 v[148:151], v138 offset:32768
	ds_read_b128 v[172:175], v139 offset:49152
	ds_read_b128 v[176:179], v139 offset:51200
	ds_read_b128 v[152:155], v138 offset:34816
	ds_read_b128 v[180:183], v139 offset:53248
	ds_read_b128 v[184:187], v139 offset:55296
	ds_read_b128 v[156:159], v138 offset:36864
	ds_read_b128 v[168:171], v138 offset:38912
	s_waitcnt lgkmcnt(8)
	v_mfma_f32_16x16x32_bf16 v[62:65], v[66:69], v[82:85], v[62:65]
	v_mfma_f32_16x16x32_bf16 v[58:61], v[66:69], v[86:89], v[58:61]
	v_mfma_f32_16x16x32_bf16 v[54:57], v[66:69], v[90:93], v[54:57]
	v_mfma_f32_16x16x32_bf16 v[50:53], v[66:69], v[94:97], v[50:53]
	v_mfma_f32_16x16x32_bf16 v[46:49], v[70:73], v[82:85], v[46:49]
	v_mfma_f32_16x16x32_bf16 v[42:45], v[70:73], v[86:89], v[42:45]
	v_mfma_f32_16x16x32_bf16 v[34:37], v[70:73], v[90:93], v[34:37]
	v_mfma_f32_16x16x32_bf16 v[30:33], v[70:73], v[94:97], v[30:33]
	v_mfma_f32_16x16x32_bf16 v[26:29], v[74:77], v[82:85], v[26:29]
	v_mfma_f32_16x16x32_bf16 v[22:25], v[74:77], v[86:89], v[22:25]
	v_mfma_f32_16x16x32_bf16 v[18:21], v[74:77], v[90:93], v[18:21]
	v_mfma_f32_16x16x32_bf16 v[14:17], v[74:77], v[94:97], v[14:17]
	v_mfma_f32_16x16x32_bf16 v[10:13], v[78:81], v[82:85], v[10:13]
	v_mfma_f32_16x16x32_bf16 v[6:9], v[78:81], v[86:89], v[6:9]
	v_mfma_f32_16x16x32_bf16 v[2:5], v[78:81], v[90:93], v[2:5]
	v_mfma_f32_16x16x32_bf16 v[38:41], v[78:81], v[94:97], v[38:41]
	s_waitcnt lgkmcnt(0)
	v_mfma_f32_16x16x32_bf16 v[62:65], v[148:151], v[172:175], v[62:65]
	v_mfma_f32_16x16x32_bf16 v[58:61], v[148:151], v[176:179], v[58:61]
	v_mfma_f32_16x16x32_bf16 v[54:57], v[148:151], v[180:183], v[54:57]
	v_mfma_f32_16x16x32_bf16 v[50:53], v[148:151], v[184:187], v[50:53]
	v_mfma_f32_16x16x32_bf16 v[46:49], v[152:155], v[172:175], v[46:49]
	v_mfma_f32_16x16x32_bf16 v[42:45], v[152:155], v[176:179], v[42:45]
	v_mfma_f32_16x16x32_bf16 v[34:37], v[152:155], v[180:183], v[34:37]
	v_mfma_f32_16x16x32_bf16 v[30:33], v[152:155], v[184:187], v[30:33]
	s_waitcnt vmcnt(0)
	s_barrier
	ds_read_b128 v[66:69], v136 offset:0
	ds_read_b128 v[82:85], v137 offset:16384
	ds_read_b128 v[86:89], v137 offset:18432
	ds_read_b128 v[70:73], v136 offset:2048
	ds_read_b128 v[90:93], v137 offset:20480
	ds_read_b128 v[94:97], v137 offset:22528
	ds_read_b128 v[74:77], v136 offset:4096
	ds_read_b128 v[78:81], v136 offset:6144
	s_add_u32 m0, s64, 0x8000
	v_mfma_f32_16x16x32_bf16 v[26:29], v[156:159], v[172:175], v[26:29]
	global_load_lds_dwordx4 v140, s[60:61]
	s_add_u32 m0, s64, 0x9000
	v_mfma_f32_16x16x32_bf16 v[22:25], v[156:159], v[176:179], v[22:25]
	global_load_lds_dwordx4 v141, s[60:61]
	s_add_u32 m0, s64, 0xa000
	v_mfma_f32_16x16x32_bf16 v[18:21], v[156:159], v[180:183], v[18:21]
	global_load_lds_dwordx4 v142, s[60:61]
	s_add_u32 m0, s64, 0xb000
	v_mfma_f32_16x16x32_bf16 v[14:17], v[156:159], v[184:187], v[14:17]
	global_load_lds_dwordx4 v143, s[60:61]
	s_add_u32 m0, s64, 0xc000
	v_mfma_f32_16x16x32_bf16 v[10:13], v[168:171], v[172:175], v[10:13]
	global_load_lds_dwordx4 v144, s[62:63]
	s_add_u32 m0, s64, 0xd000
	v_mfma_f32_16x16x32_bf16 v[6:9], v[168:171], v[176:179], v[6:9]
	global_load_lds_dwordx4 v145, s[62:63]
	s_add_u32 m0, s64, 0xe000
	v_mfma_f32_16x16x32_bf16 v[2:5], v[168:171], v[180:183], v[2:5]
	global_load_lds_dwordx4 v146, s[62:63]
	s_add_u32 m0, s64, 0xf000
	v_mfma_f32_16x16x32_bf16 v[38:41], v[168:171], v[184:187], v[38:41]
	global_load_lds_dwordx4 v147, s[62:63]
	s_add_u32 s60, s60, 0x80
	s_addc_u32 s61, s61, 0
	s_add_u32 s62, s62, 0x80
	s_addc_u32 s63, s63, 0
	s_sub_i32 s65, s65, 1
	s_cmp_lg_u32 s65, 0
	s_cbranch_scc1 .Lodwin_loop
	ds_read_b128 v[148:151], v138 offset:0
	ds_read_b128 v[172:175], v139 offset:16384
	ds_read_b128 v[176:179], v139 offset:18432
	ds_read_b128 v[152:155], v138 offset:2048
	ds_read_b128 v[180:183], v139 offset:20480
	ds_read_b128 v[184:187], v139 offset:22528
	ds_read_b128 v[156:159], v138 offset:4096
	ds_read_b128 v[168:171], v138 offset:6144
	s_waitcnt lgkmcnt(8)
	v_mfma_f32_16x16x32_bf16 v[62:65], v[66:69], v[82:85], v[62:65]
	v_mfma_f32_16x16x32_bf16 v[58:61], v[66:69], v[86:89], v[58:61]
	v_mfma_f32_16x16x32_bf16 v[54:57], v[66:69], v[90:93], v[54:57]
	v_mfma_f32_16x16x32_bf16 v[50:53], v[66:69], v[94:97], v[50:53]
	v_mfma_f32_16x16x32_bf16 v[46:49], v[70:73], v[82:85], v[46:49]
	v_mfma_f32_16x16x32_bf16 v[42:45], v[70:73], v[86:89], v[42:45]
	v_mfma_f32_16x16x32_bf16 v[34:37], v[70:73], v[90:93], v[34:37]
	v_mfma_f32_16x16x32_bf16 v[30:33], v[70:73], v[94:97], v[30:33]
	v_mfma_f32_16x16x32_bf16 v[26:29], v[74:77], v[82:85], v[26:29]
	v_mfma_f32_16x16x32_bf16 v[22:25], v[74:77], v[86:89], v[22:25]
	v_mfma_f32_16x16x32_bf16 v[18:21], v[74:77], v[90:93], v[18:21]
	v_mfma_f32_16x16x32_bf16 v[14:17], v[74:77], v[94:97], v[14:17]
	v_mfma_f32_16x16x32_bf16 v[10:13], v[78:81], v[82:85], v[10:13]
	v_mfma_f32_16x16x32_bf16 v[6:9], v[78:81], v[86:89], v[6:9]
	v_mfma_f32_16x16x32_bf16 v[2:5], v[78:81], v[90:93], v[2:5]
	v_mfma_f32_16x16x32_bf16 v[38:41], v[78:81], v[94:97], v[38:41]
	s_waitcnt lgkmcnt(0)
	v_mfma_f32_16x16x32_bf16 v[62:65], v[148:151], v[172:175], v[62:65]
	v_mfma_f32_16x16x32_bf16 v[58:61], v[148:151], v[176:179], v[58:61]
	v_mfma_f32_16x16x32_bf16 v[54:57], v[148:151], v[180:183], v[54:57]
	v_mfma_f32_16x16x32_bf16 v[50:53], v[148:151], v[184:187], v[50:53]
	v_mfma_f32_16x16x32_bf16 v[46:49], v[152:155], v[172:175], v[46:49]
	v_mfma_f32_16x16x32_bf16 v[42:45], v[152:155], v[176:179], v[42:45]
	v_mfma_f32_16x16x32_bf16 v[34:37], v[152:155], v[180:183], v[34:37]
	v_mfma_f32_16x16x32_bf16 v[30:33], v[152:155], v[184:187], v[30:33]
	s_waitcnt vmcnt(0)
	s_barrier
	ds_read_b128 v[66:69], v136 offset:32768
	ds_read_b128 v[82:85], v137 offset:49152
	ds_read_b128 v[86:89], v137 offset:51200
	ds_read_b128 v[70:73], v136 offset:34816
	ds_read_b128 v[90:93], v137 offset:53248
	ds_read_b128 v[94:97], v137 offset:55296
	ds_read_b128 v[74:77], v136 offset:36864
	ds_read_b128 v[78:81], v136 offset:38912
	v_mfma_f32_16x16x32_bf16 v[26:29], v[156:159], v[172:175], v[26:29]
	v_mfma_f32_16x16x32_bf16 v[22:25], v[156:159], v[176:179], v[22:25]
	v_mfma_f32_16x16x32_bf16 v[18:21], v[156:159], v[180:183], v[18:21]
	v_mfma_f32_16x16x32_bf16 v[14:17], v[156:159], v[184:187], v[14:17]
	v_mfma_f32_16x16x32_bf16 v[10:13], v[168:171], v[172:175], v[10:13]
	v_mfma_f32_16x16x32_bf16 v[6:9], v[168:171], v[176:179], v[6:9]
	v_mfma_f32_16x16x32_bf16 v[2:5], v[168:171], v[180:183], v[2:5]
	v_mfma_f32_16x16x32_bf16 v[38:41], v[168:171], v[184:187], v[38:41]
	ds_read_b128 v[148:151], v138 offset:32768
	ds_read_b128 v[172:175], v139 offset:49152
	ds_read_b128 v[176:179], v139 offset:51200
	ds_read_b128 v[152:155], v138 offset:34816
	ds_read_b128 v[180:183], v139 offset:53248
	ds_read_b128 v[184:187], v139 offset:55296
	ds_read_b128 v[156:159], v138 offset:36864
	ds_read_b128 v[168:171], v138 offset:38912
	s_waitcnt lgkmcnt(8)
	v_mfma_f32_16x16x32_bf16 v[62:65], v[66:69], v[82:85], v[62:65]
	v_mfma_f32_16x16x32_bf16 v[58:61], v[66:69], v[86:89], v[58:61]
	v_mfma_f32_16x16x32_bf16 v[54:57], v[66:69], v[90:93], v[54:57]
	v_mfma_f32_16x16x32_bf16 v[50:53], v[66:69], v[94:97], v[50:53]
	v_mfma_f32_16x16x32_bf16 v[46:49], v[70:73], v[82:85], v[46:49]
	v_mfma_f32_16x16x32_bf16 v[42:45], v[70:73], v[86:89], v[42:45]
	v_mfma_f32_16x16x32_bf16 v[34:37], v[70:73], v[90:93], v[34:37]
	v_mfma_f32_16x16x32_bf16 v[30:33], v[70:73], v[94:97], v[30:33]
	v_mfma_f32_16x16x32_bf16 v[26:29], v[74:77], v[82:85], v[26:29]
	v_mfma_f32_16x16x32_bf16 v[22:25], v[74:77], v[86:89], v[22:25]
	v_mfma_f32_16x16x32_bf16 v[18:21], v[74:77], v[90:93], v[18:21]
	v_mfma_f32_16x16x32_bf16 v[14:17], v[74:77], v[94:97], v[14:17]
	v_mfma_f32_16x16x32_bf16 v[10:13], v[78:81], v[82:85], v[10:13]
	v_mfma_f32_16x16x32_bf16 v[6:9], v[78:81], v[86:89], v[6:9]
	v_mfma_f32_16x16x32_bf16 v[2:5], v[78:81], v[90:93], v[2:5]
	v_mfma_f32_16x16x32_bf16 v[38:41], v[78:81], v[94:97], v[38:41]
	s_waitcnt lgkmcnt(0)
	s_barrier
	v_mfma_f32_16x16x32_bf16 v[62:65], v[148:151], v[172:175], v[62:65]
	v_mfma_f32_16x16x32_bf16 v[58:61], v[148:151], v[176:179], v[58:61]
	v_mfma_f32_16x16x32_bf16 v[54:57], v[148:151], v[180:183], v[54:57]
	v_mfma_f32_16x16x32_bf16 v[50:53], v[148:151], v[184:187], v[50:53]
	v_mfma_f32_16x16x32_bf16 v[46:49], v[152:155], v[172:175], v[46:49]
	v_mfma_f32_16x16x32_bf16 v[42:45], v[152:155], v[176:179], v[42:45]
	v_mfma_f32_16x16x32_bf16 v[34:37], v[152:155], v[180:183], v[34:37]
	v_mfma_f32_16x16x32_bf16 v[30:33], v[152:155], v[184:187], v[30:33]
	v_mfma_f32_16x16x32_bf16 v[26:29], v[156:159], v[172:175], v[26:29]
	v_mfma_f32_16x16x32_bf16 v[22:25], v[156:159], v[176:179], v[22:25]
	v_mfma_f32_16x16x32_bf16 v[18:21], v[156:159], v[180:183], v[18:21]
	v_mfma_f32_16x16x32_bf16 v[14:17], v[156:159], v[184:187], v[14:17]
	v_mfma_f32_16x16x32_bf16 v[10:13], v[168:171], v[172:175], v[10:13]
	v_mfma_f32_16x16x32_bf16 v[6:9], v[168:171], v[176:179], v[6:9]
	v_mfma_f32_16x16x32_bf16 v[2:5], v[168:171], v[180:183], v[2:5]
	v_mfma_f32_16x16x32_bf16 v[38:41], v[168:171], v[184:187], v[38:41]

.Levwin_loop:
	ds_read_b128 v[148:151], v138 offset:0
	ds_read_b128 v[172:175], v139 offset:16384
	ds_read_b128 v[176:179], v139 offset:18432
	ds_read_b128 v[152:155], v138 offset:2048
	ds_read_b128 v[180:183], v139 offset:20480
	ds_read_b128 v[184:187], v139 offset:22528
	ds_read_b128 v[156:159], v138 offset:4096
	ds_read_b128 v[168:171], v138 offset:6144
	s_waitcnt lgkmcnt(8)
	v_mfma_f32_16x16x32_bf16 v[62:65], v[66:69], v[82:85], v[62:65]
	v_mfma_f32_16x16x32_bf16 v[58:61], v[66:69], v[86:89], v[58:61]
	v_mfma_f32_16x16x32_bf16 v[54:57], v[66:69], v[90:93], v[54:57]
	v_mfma_f32_16x16x32_bf16 v[50:53], v[66:69], v[94:97], v[50:53]
	v_mfma_f32_16x16x32_bf16 v[46:49], v[70:73], v[82:85], v[46:49]
	v_mfma_f32_16x16x32_bf16 v[38:41], v[70:73], v[86:89], v[38:41]
	v_mfma_f32_16x16x32_bf16 v[34:37], v[70:73], v[90:93], v[34:37]
	v_mfma_f32_16x16x32_bf16 v[30:33], v[70:73], v[94:97], v[30:33]
	v_mfma_f32_16x16x32_bf16 v[26:29], v[74:77], v[82:85], v[26:29]
	v_mfma_f32_16x16x32_bf16 v[22:25], v[74:77], v[86:89], v[22:25]
	v_mfma_f32_16x16x32_bf16 v[18:21], v[74:77], v[90:93], v[18:21]
	v_mfma_f32_16x16x32_bf16 v[14:17], v[74:77], v[94:97], v[14:17]
	v_mfma_f32_16x16x32_bf16 v[10:13], v[78:81], v[82:85], v[10:13]
	v_mfma_f32_16x16x32_bf16 v[6:9], v[78:81], v[86:89], v[6:9]
	v_mfma_f32_16x16x32_bf16 v[2:5], v[78:81], v[90:93], v[2:5]
	v_mfma_f32_16x16x32_bf16 v[42:45], v[78:81], v[94:97], v[42:45]
	s_waitcnt lgkmcnt(0)
	v_mfma_f32_16x16x32_bf16 v[62:65], v[148:151], v[172:175], v[62:65]
	v_mfma_f32_16x16x32_bf16 v[58:61], v[148:151], v[176:179], v[58:61]
	v_mfma_f32_16x16x32_bf16 v[54:57], v[148:151], v[180:183], v[54:57]
	v_mfma_f32_16x16x32_bf16 v[50:53], v[148:151], v[184:187], v[50:53]
	v_mfma_f32_16x16x32_bf16 v[46:49], v[152:155], v[172:175], v[46:49]
	v_mfma_f32_16x16x32_bf16 v[38:41], v[152:155], v[176:179], v[38:41]
	v_mfma_f32_16x16x32_bf16 v[34:37], v[152:155], v[180:183], v[34:37]
	v_mfma_f32_16x16x32_bf16 v[30:33], v[152:155], v[184:187], v[30:33]
	s_waitcnt vmcnt(0)
	s_barrier
	ds_read_b128 v[66:69], v136 offset:32768
	ds_read_b128 v[82:85], v137 offset:49152
	ds_read_b128 v[86:89], v137 offset:51200
	ds_read_b128 v[70:73], v136 offset:34816
	ds_read_b128 v[90:93], v137 offset:53248
	ds_read_b128 v[94:97], v137 offset:55296
	ds_read_b128 v[74:77], v136 offset:36864
	ds_read_b128 v[78:81], v136 offset:38912
	s_add_u32 m0, s64, 0x0
	v_mfma_f32_16x16x32_bf16 v[26:29], v[156:159], v[172:175], v[26:29]
	global_load_lds_dwordx4 v140, s[60:61]
	s_add_u32 m0, s64, 0x1000
	v_mfma_f32_16x16x32_bf16 v[22:25], v[156:159], v[176:179], v[22:25]
	global_load_lds_dwordx4 v141, s[60:61]
	s_add_u32 m0, s64, 0x2000
	v_mfma_f32_16x16x32_bf16 v[18:21], v[156:159], v[180:183], v[18:21]
	global_load_lds_dwordx4 v142, s[60:61]
	s_add_u32 m0, s64, 0x3000
	v_mfma_f32_16x16x32_bf16 v[14:17], v[156:159], v[184:187], v[14:17]
	global_load_lds_dwordx4 v143, s[60:61]
	s_add_u32 m0, s64, 0x4000
	v_mfma_f32_16x16x32_bf16 v[10:13], v[168:171], v[172:175], v[10:13]
	global_load_lds_dwordx4 v144, s[62:63]
	s_add_u32 m0, s64, 0x5000
	v_mfma_f32_16x16x32_bf16 v[6:9], v[168:171], v[176:179], v[6:9]
	global_load_lds_dwordx4 v145, s[62:63]
	s_add_u32 m0, s64, 0x6000
	v_mfma_f32_16x16x32_bf16 v[2:5], v[168:171], v[180:183], v[2:5]
	global_load_lds_dwordx4 v146, s[62:63]
	s_add_u32 m0, s64, 0x7000
	v_mfma_f32_16x16x32_bf16 v[42:45], v[168:171], v[184:187], v[42:45]
	global_load_lds_dwordx4 v147, s[62:63]
	s_add_u32 s60, s60, 0x80
	s_addc_u32 s61, s61, 0
	s_add_u32 s62, s62, 0x80
	s_addc_u32 s63, s63, 0
	ds_read_b128 v[148:151], v138 offset:32768
	ds_read_b128 v[172:175], v139 offset:49152
	ds_read_b128 v[176:179], v139 offset:51200
	ds_read_b128 v[152:155], v138 offset:34816
	ds_read_b128 v[180:183], v139 offset:53248
	ds_read_b128 v[184:187], v139 offset:55296
	ds_read_b128 v[156:159], v138 offset:36864
	ds_read_b128 v[168:171], v138 offset:38912
	s_waitcnt lgkmcnt(8)
	v_mfma_f32_16x16x32_bf16 v[62:65], v[66:69], v[82:85], v[62:65]
	v_mfma_f32_16x16x32_bf16 v[58:61], v[66:69], v[86:89], v[58:61]
	v_mfma_f32_16x16x32_bf16 v[54:57], v[66:69], v[90:93], v[54:57]
	v_mfma_f32_16x16x32_bf16 v[50:53], v[66:69], v[94:97], v[50:53]
	v_mfma_f32_16x16x32_bf16 v[46:49], v[70:73], v[82:85], v[46:49]
	v_mfma_f32_16x16x32_bf16 v[38:41], v[70:73], v[86:89], v[38:41]
	v_mfma_f32_16x16x32_bf16 v[34:37], v[70:73], v[90:93], v[34:37]
	v_mfma_f32_16x16x32_bf16 v[30:33], v[70:73], v[94:97], v[30:33]
	v_mfma_f32_16x16x32_bf16 v[26:29], v[74:77], v[82:85], v[26:29]
	v_mfma_f32_16x16x32_bf16 v[22:25], v[74:77], v[86:89], v[22:25]
	v_mfma_f32_16x16x32_bf16 v[18:21], v[74:77], v[90:93], v[18:21]
	v_mfma_f32_16x16x32_bf16 v[14:17], v[74:77], v[94:97], v[14:17]
	v_mfma_f32_16x16x32_bf16 v[10:13], v[78:81], v[82:85], v[10:13]
	v_mfma_f32_16x16x32_bf16 v[6:9], v[78:81], v[86:89], v[6:9]
	v_mfma_f32_16x16x32_bf16 v[2:5], v[78:81], v[90:93], v[2:5]
	v_mfma_f32_16x16x32_bf16 v[42:45], v[78:81], v[94:97], v[42:45]
	s_waitcnt lgkmcnt(0)
	v_mfma_f32_16x16x32_bf16 v[62:65], v[148:151], v[172:175], v[62:65]
	v_mfma_f32_16x16x32_bf16 v[58:61], v[148:151], v[176:179], v[58:61]
	v_mfma_f32_16x16x32_bf16 v[54:57], v[148:151], v[180:183], v[54:57]
	v_mfma_f32_16x16x32_bf16 v[50:53], v[148:151], v[184:187], v[50:53]
	v_mfma_f32_16x16x32_bf16 v[46:49], v[152:155], v[172:175], v[46:49]
	v_mfma_f32_16x16x32_bf16 v[38:41], v[152:155], v[176:179], v[38:41]
	v_mfma_f32_16x16x32_bf16 v[34:37], v[152:155], v[180:183], v[34:37]
	v_mfma_f32_16x16x32_bf16 v[30:33], v[152:155], v[184:187], v[30:33]
	s_waitcnt vmcnt(0)
	s_barrier
	ds_read_b128 v[66:69], v136 offset:0
	ds_read_b128 v[82:85], v137 offset:16384
	ds_read_b128 v[86:89], v137 offset:18432
	ds_read_b128 v[70:73], v136 offset:2048
	ds_read_b128 v[90:93], v137 offset:20480
	ds_read_b128 v[94:97], v137 offset:22528
	ds_read_b128 v[74:77], v136 offset:4096
	ds_read_b128 v[78:81], v136 offset:6144
	s_add_u32 m0, s64, 0x8000
	v_mfma_f32_16x16x32_bf16 v[26:29], v[156:159], v[172:175], v[26:29]
	global_load_lds_dwordx4 v140, s[60:61]
	s_add_u32 m0, s64, 0x9000
	v_mfma_f32_16x16x32_bf16 v[22:25], v[156:159], v[176:179], v[22:25]
	global_load_lds_dwordx4 v141, s[60:61]
	s_add_u32 m0, s64, 0xa000
	v_mfma_f32_16x16x32_bf16 v[18:21], v[156:159], v[180:183], v[18:21]
	global_load_lds_dwordx4 v142, s[60:61]
	s_add_u32 m0, s64, 0xb000
	v_mfma_f32_16x16x32_bf16 v[14:17], v[156:159], v[184:187], v[14:17]
	global_load_lds_dwordx4 v143, s[60:61]
	s_add_u32 m0, s64, 0xc000
	v_mfma_f32_16x16x32_bf16 v[10:13], v[168:171], v[172:175], v[10:13]
	global_load_lds_dwordx4 v144, s[62:63]
	s_add_u32 m0, s64, 0xd000
	v_mfma_f32_16x16x32_bf16 v[6:9], v[168:171], v[176:179], v[6:9]
	global_load_lds_dwordx4 v145, s[62:63]
	s_add_u32 m0, s64, 0xe000
	v_mfma_f32_16x16x32_bf16 v[2:5], v[168:171], v[180:183], v[2:5]
	global_load_lds_dwordx4 v146, s[62:63]
	s_add_u32 m0, s64, 0xf000
	v_mfma_f32_16x16x32_bf16 v[42:45], v[168:171], v[184:187], v[42:45]
	global_load_lds_dwordx4 v147, s[62:63]
	s_add_u32 s60, s60, 0x80
	s_addc_u32 s61, s61, 0
	s_add_u32 s62, s62, 0x80
	s_addc_u32 s63, s63, 0
	s_sub_i32 s65, s65, 1
	s_cmp_lg_u32 s65, 0
	s_cbranch_scc1 .Levwin_loop
	ds_read_b128 v[148:151], v138 offset:0
	ds_read_b128 v[172:175], v139 offset:16384
	ds_read_b128 v[176:179], v139 offset:18432
	ds_read_b128 v[152:155], v138 offset:2048
	ds_read_b128 v[180:183], v139 offset:20480
	ds_read_b128 v[184:187], v139 offset:22528
	ds_read_b128 v[156:159], v138 offset:4096
	ds_read_b128 v[168:171], v138 offset:6144
	s_waitcnt lgkmcnt(8)
	v_mfma_f32_16x16x32_bf16 v[62:65], v[66:69], v[82:85], v[62:65]
	v_mfma_f32_16x16x32_bf16 v[58:61], v[66:69], v[86:89], v[58:61]
	v_mfma_f32_16x16x32_bf16 v[54:57], v[66:69], v[90:93], v[54:57]
	v_mfma_f32_16x16x32_bf16 v[50:53], v[66:69], v[94:97], v[50:53]
	v_mfma_f32_16x16x32_bf16 v[46:49], v[70:73], v[82:85], v[46:49]
	v_mfma_f32_16x16x32_bf16 v[38:41], v[70:73], v[86:89], v[38:41]
	v_mfma_f32_16x16x32_bf16 v[34:37], v[70:73], v[90:93], v[34:37]
	v_mfma_f32_16x16x32_bf16 v[30:33], v[70:73], v[94:97], v[30:33]
	v_mfma_f32_16x16x32_bf16 v[26:29], v[74:77], v[82:85], v[26:29]
	v_mfma_f32_16x16x32_bf16 v[22:25], v[74:77], v[86:89], v[22:25]
	v_mfma_f32_16x16x32_bf16 v[18:21], v[74:77], v[90:93], v[18:21]
	v_mfma_f32_16x16x32_bf16 v[14:17], v[74:77], v[94:97], v[14:17]
	v_mfma_f32_16x16x32_bf16 v[10:13], v[78:81], v[82:85], v[10:13]
	v_mfma_f32_16x16x32_bf16 v[6:9], v[78:81], v[86:89], v[6:9]
	v_mfma_f32_16x16x32_bf16 v[2:5], v[78:81], v[90:93], v[2:5]
	v_mfma_f32_16x16x32_bf16 v[42:45], v[78:81], v[94:97], v[42:45]
	s_waitcnt lgkmcnt(0)
	v_mfma_f32_16x16x32_bf16 v[62:65], v[148:151], v[172:175], v[62:65]
	v_mfma_f32_16x16x32_bf16 v[58:61], v[148:151], v[176:179], v[58:61]
	v_mfma_f32_16x16x32_bf16 v[54:57], v[148:151], v[180:183], v[54:57]
	v_mfma_f32_16x16x32_bf16 v[50:53], v[148:151], v[184:187], v[50:53]
	v_mfma_f32_16x16x32_bf16 v[46:49], v[152:155], v[172:175], v[46:49]
	v_mfma_f32_16x16x32_bf16 v[38:41], v[152:155], v[176:179], v[38:41]
	v_mfma_f32_16x16x32_bf16 v[34:37], v[152:155], v[180:183], v[34:37]
	v_mfma_f32_16x16x32_bf16 v[30:33], v[152:155], v[184:187], v[30:33]
	s_waitcnt vmcnt(0)
	s_barrier
	ds_read_b128 v[66:69], v136 offset:32768
	ds_read_b128 v[82:85], v137 offset:49152
	ds_read_b128 v[86:89], v137 offset:51200
	ds_read_b128 v[70:73], v136 offset:34816
	ds_read_b128 v[90:93], v137 offset:53248
	ds_read_b128 v[94:97], v137 offset:55296
	ds_read_b128 v[74:77], v136 offset:36864
	ds_read_b128 v[78:81], v136 offset:38912
	v_mfma_f32_16x16x32_bf16 v[26:29], v[156:159], v[172:175], v[26:29]
	v_mfma_f32_16x16x32_bf16 v[22:25], v[156:159], v[176:179], v[22:25]
	v_mfma_f32_16x16x32_bf16 v[18:21], v[156:159], v[180:183], v[18:21]
	v_mfma_f32_16x16x32_bf16 v[14:17], v[156:159], v[184:187], v[14:17]
	v_mfma_f32_16x16x32_bf16 v[10:13], v[168:171], v[172:175], v[10:13]
	v_mfma_f32_16x16x32_bf16 v[6:9], v[168:171], v[176:179], v[6:9]
	v_mfma_f32_16x16x32_bf16 v[2:5], v[168:171], v[180:183], v[2:5]
	v_mfma_f32_16x16x32_bf16 v[42:45], v[168:171], v[184:187], v[42:45]
	ds_read_b128 v[148:151], v138 offset:32768
	ds_read_b128 v[172:175], v139 offset:49152
	ds_read_b128 v[176:179], v139 offset:51200
	ds_read_b128 v[152:155], v138 offset:34816
	ds_read_b128 v[180:183], v139 offset:53248
	ds_read_b128 v[184:187], v139 offset:55296
	ds_read_b128 v[156:159], v138 offset:36864
	ds_read_b128 v[168:171], v138 offset:38912
	s_waitcnt lgkmcnt(8)
	v_mfma_f32_16x16x32_bf16 v[62:65], v[66:69], v[82:85], v[62:65]
	v_mfma_f32_16x16x32_bf16 v[58:61], v[66:69], v[86:89], v[58:61]
	v_mfma_f32_16x16x32_bf16 v[54:57], v[66:69], v[90:93], v[54:57]
	v_mfma_f32_16x16x32_bf16 v[50:53], v[66:69], v[94:97], v[50:53]
	v_mfma_f32_16x16x32_bf16 v[46:49], v[70:73], v[82:85], v[46:49]
	v_mfma_f32_16x16x32_bf16 v[38:41], v[70:73], v[86:89], v[38:41]
	v_mfma_f32_16x16x32_bf16 v[34:37], v[70:73], v[90:93], v[34:37]
	v_mfma_f32_16x16x32_bf16 v[30:33], v[70:73], v[94:97], v[30:33]
	v_mfma_f32_16x16x32_bf16 v[26:29], v[74:77], v[82:85], v[26:29]
	v_mfma_f32_16x16x32_bf16 v[22:25], v[74:77], v[86:89], v[22:25]
	v_mfma_f32_16x16x32_bf16 v[18:21], v[74:77], v[90:93], v[18:21]
	v_mfma_f32_16x16x32_bf16 v[14:17], v[74:77], v[94:97], v[14:17]
	v_mfma_f32_16x16x32_bf16 v[10:13], v[78:81], v[82:85], v[10:13]
	v_mfma_f32_16x16x32_bf16 v[6:9], v[78:81], v[86:89], v[6:9]
	v_mfma_f32_16x16x32_bf16 v[2:5], v[78:81], v[90:93], v[2:5]
	v_mfma_f32_16x16x32_bf16 v[42:45], v[78:81], v[94:97], v[42:45]
	s_waitcnt lgkmcnt(0)
	s_barrier
	v_mfma_f32_16x16x32_bf16 v[62:65], v[148:151], v[172:175], v[62:65]
	v_mfma_f32_16x16x32_bf16 v[58:61], v[148:151], v[176:179], v[58:61]
	v_mfma_f32_16x16x32_bf16 v[54:57], v[148:151], v[180:183], v[54:57]
	v_mfma_f32_16x16x32_bf16 v[50:53], v[148:151], v[184:187], v[50:53]
	v_mfma_f32_16x16x32_bf16 v[46:49], v[152:155], v[172:175], v[46:49]
	v_mfma_f32_16x16x32_bf16 v[38:41], v[152:155], v[176:179], v[38:41]
	v_mfma_f32_16x16x32_bf16 v[34:37], v[152:155], v[180:183], v[34:37]
	v_mfma_f32_16x16x32_bf16 v[30:33], v[152:155], v[184:187], v[30:33]
	v_mfma_f32_16x16x32_bf16 v[26:29], v[156:159], v[172:175], v[26:29]
	v_mfma_f32_16x16x32_bf16 v[22:25], v[156:159], v[176:179], v[22:25]
	v_mfma_f32_16x16x32_bf16 v[18:21], v[156:159], v[180:183], v[18:21]
	v_mfma_f32_16x16x32_bf16 v[14:17], v[156:159], v[184:187], v[14:17]
	v_mfma_f32_16x16x32_bf16 v[10:13], v[168:171], v[172:175], v[10:13]
	v_mfma_f32_16x16x32_bf16 v[6:9], v[168:171], v[176:179], v[6:9]
	v_mfma_f32_16x16x32_bf16 v[2:5], v[168:171], v[180:183], v[2:5]
	v_mfma_f32_16x16x32_bf16 v[42:45], v[168:171], v[184:187], v[42:45]
